# V3 + nt hint on the streamed ACT stores of the two SwiGLU GEMM epilogues
# baseline (speedup 1.0000x reference)
.LBB0_145:
	v_mul_f32_e32 v168, 0xbfb8aa3b, v120
	v_mul_f32_e32 v169, 0xbfb8aa3b, v116
	v_mul_f32_e32 v170, 0xbfb8aa3b, v121
	v_exp_f32_e32 v168, v168
	v_exp_f32_e32 v169, v169
	v_exp_f32_e32 v170, v170
	s_lshl_b32 s20, s51, 1
	v_add_f32_e32 v168, 1.0, v168
	v_add_f32_e32 v171, 1.0, v169
	v_add_f32_e32 v169, 1.0, v170
	v_rcp_f32_e32 v168, v168
	v_rcp_f32_e32 v169, v169
	v_mul_f32_e32 v170, 0xbfb8aa3b, v117
	v_exp_f32_e32 v172, v170
	v_rcp_f32_e32 v170, v171
	v_pk_mul_f32 v[120:121], v[120:121], v[168:169]
	v_mul_f32_e32 v168, 0xbfb8aa3b, v123
	v_pk_mul_f32 v[120:121], v[124:125], v[120:121]
	v_add_f32_e32 v124, 1.0, v172
	v_rcp_f32_e32 v171, v124
	v_mul_f32_e32 v125, 0xbfb8aa3b, v118
	v_mul_f32_e32 v124, 0xbfb8aa3b, v122
	v_exp_f32_e32 v125, v125
	v_exp_f32_e32 v124, v124
	v_exp_f32_e32 v169, v168
	v_mul_f32_e32 v168, 0xbfb8aa3b, v119
	v_pk_mul_f32 v[116:117], v[116:117], v[170:171]
	v_exp_f32_e32 v170, v168
	v_add_f32_e32 v125, 1.0, v125
	s_or_b32 s20, s20, s43
	v_add_f32_e32 v124, 1.0, v124
	v_rcp_f32_e32 v168, v125
	v_add_f32_e32 v125, 1.0, v169
	s_mul_i32 s22, s50, 0x58
	s_ashr_i32 s23, s20, 31
	v_rcp_f32_e32 v124, v124
	v_rcp_f32_e32 v125, v125
	v_add_f32_e32 v169, 1.0, v170
	s_mul_hi_i32 s21, s50, 0x58
	s_add_u32 s20, s22, s20
	v_rcp_f32_e32 v169, v169
	s_addc_u32 s21, s21, s23
	s_lshl_b64 s[20:21], s[20:21], 15
	v_pk_mul_f32 v[116:117], v[112:113], v[116:117]
	v_pk_mul_f32 v[112:113], v[122:123], v[124:125]
	s_add_u32 s20, s37, s20
	v_pk_mul_f32 v[122:123], v[126:127], v[112:113]
	v_pk_mul_f32 v[112:113], v[118:119], v[168:169]
	s_addc_u32 s21, s38, s21
	v_pk_mul_f32 v[118:119], v[114:115], v[112:113]
	v_cvt_pk_bf16_f32 v114, v116, v117
	v_lshl_add_u64 v[116:117], s[20:21], 0, v[138:139]
	v_cvt_pk_bf16_f32 v112, v120, v121
	v_cvt_pk_bf16_f32 v113, v122, v123
	v_cvt_pk_bf16_f32 v115, v118, v119
	v_lshl_add_u64 v[116:117], v[116:117], 0, v[136:137]
	global_store_dwordx4 v[116:117], v[112:115], off nt
	s_and_b64 vcc, exec, s[2:3]
	s_mov_b64 s[2:3], -1
	v_mul_f32_e32 v112, 0xbfb8aa3b, v108
	v_mul_f32_e32 v113, 0xbfb8aa3b, v100
	v_mul_f32_e32 v114, 0xbfb8aa3b, v109
	v_exp_f32_e32 v112, v112
	v_exp_f32_e32 v113, v113
	v_exp_f32_e32 v114, v114
	v_add_f32_e32 v112, 1.0, v112
	v_add_f32_e32 v115, 1.0, v113
	v_add_f32_e32 v113, 1.0, v114
	v_rcp_f32_e32 v112, v112
	v_rcp_f32_e32 v113, v113
	v_mul_f32_e32 v114, 0xbfb8aa3b, v101
	v_exp_f32_e32 v116, v114
	v_rcp_f32_e32 v114, v115
	v_pk_mul_f32 v[108:109], v[108:109], v[112:113]
	v_mul_f32_e32 v112, 0xbfb8aa3b, v111
	v_pk_mul_f32 v[104:105], v[104:105], v[108:109]
	v_add_f32_e32 v108, 1.0, v116
	v_rcp_f32_e32 v115, v108
	v_mul_f32_e32 v109, 0xbfb8aa3b, v102
	v_mul_f32_e32 v108, 0xbfb8aa3b, v110
	v_exp_f32_e32 v109, v109
	v_exp_f32_e32 v108, v108
	v_exp_f32_e32 v113, v112
	v_mul_f32_e32 v112, 0xbfb8aa3b, v103
	v_pk_mul_f32 v[100:101], v[100:101], v[114:115]
	v_exp_f32_e32 v114, v112
	v_add_f32_e32 v109, 1.0, v109
	v_add_f32_e32 v108, 1.0, v108
	v_rcp_f32_e32 v112, v109
	v_add_f32_e32 v109, 1.0, v113
	v_rcp_f32_e32 v108, v108
	v_rcp_f32_e32 v109, v109
	v_add_f32_e32 v113, 1.0, v114
	v_rcp_f32_e32 v113, v113
	v_pk_mul_f32 v[100:101], v[96:97], v[100:101]
	v_pk_mul_f32 v[96:97], v[110:111], v[108:109]
	s_nop 0
	v_pk_mul_f32 v[106:107], v[106:107], v[96:97]
	v_pk_mul_f32 v[96:97], v[102:103], v[112:113]
	s_nop 0
	v_pk_mul_f32 v[102:103], v[98:99], v[96:97]
	v_cvt_pk_bf16_f32 v98, v100, v101
	v_lshl_add_u64 v[100:101], s[20:21], 0, v[140:141]
	v_cvt_pk_bf16_f32 v96, v104, v105
	v_cvt_pk_bf16_f32 v97, v106, v107
	v_cvt_pk_bf16_f32 v99, v102, v103
	v_lshl_add_u64 v[100:101], v[100:101], 0, v[136:137]
	global_store_dwordx4 v[100:101], v[96:99], off nt
	s_nop 1
	v_mul_f32_e32 v96, 0xbfb8aa3b, v92
	v_mul_f32_e32 v97, 0xbfb8aa3b, v84
	v_mul_f32_e32 v98, 0xbfb8aa3b, v93
	v_exp_f32_e32 v96, v96
	v_exp_f32_e32 v97, v97
	v_exp_f32_e32 v98, v98
	v_add_f32_e32 v96, 1.0, v96
	v_add_f32_e32 v99, 1.0, v97
	v_add_f32_e32 v97, 1.0, v98
	v_rcp_f32_e32 v96, v96
	v_rcp_f32_e32 v97, v97
	v_mul_f32_e32 v98, 0xbfb8aa3b, v85
	v_exp_f32_e32 v100, v98
	v_rcp_f32_e32 v98, v99
	v_pk_mul_f32 v[92:93], v[92:93], v[96:97]
	v_mul_f32_e32 v96, 0xbfb8aa3b, v95
	v_pk_mul_f32 v[88:89], v[88:89], v[92:93]
	v_add_f32_e32 v92, 1.0, v100
	v_rcp_f32_e32 v99, v92
	v_mul_f32_e32 v93, 0xbfb8aa3b, v86
	v_mul_f32_e32 v92, 0xbfb8aa3b, v94
	v_exp_f32_e32 v93, v93
	v_exp_f32_e32 v92, v92
	v_exp_f32_e32 v97, v96
	v_mul_f32_e32 v96, 0xbfb8aa3b, v87
	v_pk_mul_f32 v[84:85], v[84:85], v[98:99]
	v_exp_f32_e32 v98, v96
	v_add_f32_e32 v93, 1.0, v93
	v_add_f32_e32 v92, 1.0, v92
	v_rcp_f32_e32 v96, v93
	v_add_f32_e32 v93, 1.0, v97
	v_rcp_f32_e32 v92, v92
	v_rcp_f32_e32 v93, v93
	v_add_f32_e32 v97, 1.0, v98
	v_rcp_f32_e32 v97, v97
	v_pk_mul_f32 v[84:85], v[80:81], v[84:85]
	v_pk_mul_f32 v[80:81], v[94:95], v[92:93]
	s_nop 0
	v_pk_mul_f32 v[90:91], v[90:91], v[80:81]
	v_pk_mul_f32 v[80:81], v[86:87], v[96:97]
	s_nop 0
	v_pk_mul_f32 v[86:87], v[82:83], v[80:81]
	v_cvt_pk_bf16_f32 v82, v84, v85
	v_lshl_add_u64 v[84:85], s[20:21], 0, v[142:143]
	v_cvt_pk_bf16_f32 v80, v88, v89
	v_cvt_pk_bf16_f32 v81, v90, v91
	v_cvt_pk_bf16_f32 v83, v86, v87
	v_lshl_add_u64 v[84:85], v[84:85], 0, v[136:137]
	global_store_dwordx4 v[84:85], v[80:83], off nt
	s_nop 1
	v_mul_f32_e32 v80, 0xbfb8aa3b, v76
	v_mul_f32_e32 v81, 0xbfb8aa3b, v68
	v_mul_f32_e32 v82, 0xbfb8aa3b, v77
	v_exp_f32_e32 v80, v80
	v_exp_f32_e32 v81, v81
	v_exp_f32_e32 v82, v82
	v_add_f32_e32 v80, 1.0, v80
	v_add_f32_e32 v83, 1.0, v81
	v_add_f32_e32 v81, 1.0, v82
	v_rcp_f32_e32 v80, v80
	v_rcp_f32_e32 v81, v81
	v_mul_f32_e32 v82, 0xbfb8aa3b, v69
	v_exp_f32_e32 v84, v82
	v_rcp_f32_e32 v82, v83
	v_pk_mul_f32 v[76:77], v[76:77], v[80:81]
	v_mul_f32_e32 v80, 0xbfb8aa3b, v79
	v_pk_mul_f32 v[72:73], v[72:73], v[76:77]
	v_add_f32_e32 v76, 1.0, v84
	v_rcp_f32_e32 v83, v76
	v_mul_f32_e32 v77, 0xbfb8aa3b, v70
	v_mul_f32_e32 v76, 0xbfb8aa3b, v78
	v_exp_f32_e32 v77, v77
	v_exp_f32_e32 v76, v76
	v_exp_f32_e32 v81, v80
	v_mul_f32_e32 v80, 0xbfb8aa3b, v71
	v_pk_mul_f32 v[68:69], v[68:69], v[82:83]
	v_exp_f32_e32 v82, v80
	v_add_f32_e32 v77, 1.0, v77
	v_add_f32_e32 v76, 1.0, v76
	v_rcp_f32_e32 v80, v77
	v_add_f32_e32 v77, 1.0, v81
	v_rcp_f32_e32 v76, v76
	v_rcp_f32_e32 v77, v77
	v_add_f32_e32 v81, 1.0, v82
	v_rcp_f32_e32 v81, v81
	v_pk_mul_f32 v[68:69], v[64:65], v[68:69]
	v_pk_mul_f32 v[64:65], v[78:79], v[76:77]
	s_nop 0
	v_pk_mul_f32 v[74:75], v[74:75], v[64:65]
	v_pk_mul_f32 v[64:65], v[70:71], v[80:81]
	s_nop 0
	v_pk_mul_f32 v[70:71], v[66:67], v[64:65]
	v_cvt_pk_bf16_f32 v66, v68, v69
	v_lshl_add_u64 v[68:69], s[20:21], 0, v[144:145]
	v_cvt_pk_bf16_f32 v64, v72, v73
	v_cvt_pk_bf16_f32 v65, v74, v75
	v_cvt_pk_bf16_f32 v67, v70, v71
	v_lshl_add_u64 v[68:69], v[68:69], 0, v[136:137]
	global_store_dwordx4 v[68:69], v[64:67], off nt
	s_nop 1
	v_mul_f32_e32 v64, 0xbfb8aa3b, v60
	v_mul_f32_e32 v65, 0xbfb8aa3b, v52
	v_mul_f32_e32 v66, 0xbfb8aa3b, v61
	v_exp_f32_e32 v64, v64
	v_exp_f32_e32 v65, v65
	v_exp_f32_e32 v66, v66
	v_add_f32_e32 v64, 1.0, v64
	v_add_f32_e32 v67, 1.0, v65
	v_add_f32_e32 v65, 1.0, v66
	v_rcp_f32_e32 v64, v64
	v_rcp_f32_e32 v65, v65
	v_mul_f32_e32 v66, 0xbfb8aa3b, v53
	v_exp_f32_e32 v68, v66
	v_rcp_f32_e32 v66, v67
	v_pk_mul_f32 v[60:61], v[60:61], v[64:65]
	v_mul_f32_e32 v64, 0xbfb8aa3b, v63
	v_pk_mul_f32 v[56:57], v[56:57], v[60:61]
	v_add_f32_e32 v60, 1.0, v68
	v_rcp_f32_e32 v67, v60
	v_mul_f32_e32 v61, 0xbfb8aa3b, v54
	v_mul_f32_e32 v60, 0xbfb8aa3b, v62
	v_exp_f32_e32 v61, v61
	v_exp_f32_e32 v60, v60
	v_exp_f32_e32 v65, v64
	v_mul_f32_e32 v64, 0xbfb8aa3b, v55
	v_pk_mul_f32 v[52:53], v[52:53], v[66:67]
	v_exp_f32_e32 v66, v64
	v_add_f32_e32 v61, 1.0, v61
	v_add_f32_e32 v60, 1.0, v60
	v_rcp_f32_e32 v64, v61
	v_add_f32_e32 v61, 1.0, v65
	v_rcp_f32_e32 v60, v60
	v_rcp_f32_e32 v61, v61
	v_add_f32_e32 v65, 1.0, v66
	v_rcp_f32_e32 v65, v65
	v_pk_mul_f32 v[52:53], v[48:49], v[52:53]
	v_pk_mul_f32 v[48:49], v[62:63], v[60:61]
	s_nop 0
	v_pk_mul_f32 v[58:59], v[58:59], v[48:49]
	v_pk_mul_f32 v[48:49], v[54:55], v[64:65]
	s_nop 0
	v_pk_mul_f32 v[54:55], v[50:51], v[48:49]
	v_cvt_pk_bf16_f32 v50, v52, v53
	v_lshl_add_u64 v[52:53], s[20:21], 0, v[146:147]
	v_cvt_pk_bf16_f32 v48, v56, v57
	v_cvt_pk_bf16_f32 v49, v58, v59
	v_cvt_pk_bf16_f32 v51, v54, v55
	v_lshl_add_u64 v[52:53], v[52:53], 0, v[136:137]
	global_store_dwordx4 v[52:53], v[48:51], off nt
	s_nop 1
	v_mul_f32_e32 v48, 0xbfb8aa3b, v44
	v_mul_f32_e32 v49, 0xbfb8aa3b, v36
	v_mul_f32_e32 v50, 0xbfb8aa3b, v45
	v_exp_f32_e32 v48, v48
	v_exp_f32_e32 v49, v49
	v_exp_f32_e32 v50, v50
	v_add_f32_e32 v48, 1.0, v48
	v_add_f32_e32 v51, 1.0, v49
	v_add_f32_e32 v49, 1.0, v50
	v_rcp_f32_e32 v48, v48
	v_rcp_f32_e32 v49, v49
	v_mul_f32_e32 v50, 0xbfb8aa3b, v37
	v_exp_f32_e32 v52, v50
	v_rcp_f32_e32 v50, v51
	v_pk_mul_f32 v[44:45], v[44:45], v[48:49]
	v_mul_f32_e32 v48, 0xbfb8aa3b, v47
	v_pk_mul_f32 v[40:41], v[40:41], v[44:45]
	v_add_f32_e32 v44, 1.0, v52
	v_rcp_f32_e32 v51, v44
	v_mul_f32_e32 v45, 0xbfb8aa3b, v38
	v_mul_f32_e32 v44, 0xbfb8aa3b, v46
	v_exp_f32_e32 v45, v45
	v_exp_f32_e32 v44, v44
	v_exp_f32_e32 v49, v48
	v_mul_f32_e32 v48, 0xbfb8aa3b, v39
	v_pk_mul_f32 v[36:37], v[36:37], v[50:51]
	v_exp_f32_e32 v50, v48
	v_add_f32_e32 v45, 1.0, v45
	v_add_f32_e32 v44, 1.0, v44
	v_rcp_f32_e32 v48, v45
	v_add_f32_e32 v45, 1.0, v49
	v_rcp_f32_e32 v44, v44
	v_rcp_f32_e32 v45, v45
	v_add_f32_e32 v49, 1.0, v50
	v_rcp_f32_e32 v49, v49
	v_pk_mul_f32 v[36:37], v[32:33], v[36:37]
	v_pk_mul_f32 v[32:33], v[46:47], v[44:45]
	s_nop 0
	v_pk_mul_f32 v[42:43], v[42:43], v[32:33]
	v_pk_mul_f32 v[32:33], v[38:39], v[48:49]
	s_nop 0
	v_pk_mul_f32 v[38:39], v[34:35], v[32:33]
	v_cvt_pk_bf16_f32 v34, v36, v37
	v_lshl_add_u64 v[36:37], s[20:21], 0, v[148:149]
	v_cvt_pk_bf16_f32 v32, v40, v41
	v_cvt_pk_bf16_f32 v33, v42, v43
	v_cvt_pk_bf16_f32 v35, v38, v39
	v_lshl_add_u64 v[36:37], v[36:37], 0, v[136:137]
	global_store_dwordx4 v[36:37], v[32:35], off nt
	s_nop 1
	v_mul_f32_e32 v32, 0xbfb8aa3b, v28
	v_mul_f32_e32 v33, 0xbfb8aa3b, v20
	v_mul_f32_e32 v34, 0xbfb8aa3b, v29
	v_exp_f32_e32 v32, v32
	v_exp_f32_e32 v33, v33
	v_exp_f32_e32 v34, v34
	v_add_f32_e32 v32, 1.0, v32
	v_add_f32_e32 v35, 1.0, v33
	v_add_f32_e32 v33, 1.0, v34
	v_rcp_f32_e32 v32, v32
	v_rcp_f32_e32 v33, v33
	v_mul_f32_e32 v34, 0xbfb8aa3b, v21
	v_exp_f32_e32 v36, v34
	v_rcp_f32_e32 v34, v35
	v_pk_mul_f32 v[28:29], v[28:29], v[32:33]
	v_mul_f32_e32 v32, 0xbfb8aa3b, v31
	v_pk_mul_f32 v[24:25], v[24:25], v[28:29]
	v_add_f32_e32 v28, 1.0, v36
	v_rcp_f32_e32 v35, v28
	v_mul_f32_e32 v29, 0xbfb8aa3b, v22
	v_mul_f32_e32 v28, 0xbfb8aa3b, v30
	v_exp_f32_e32 v29, v29
	v_exp_f32_e32 v28, v28
	v_exp_f32_e32 v33, v32
	v_mul_f32_e32 v32, 0xbfb8aa3b, v23
	v_pk_mul_f32 v[20:21], v[20:21], v[34:35]
	v_exp_f32_e32 v34, v32
	v_add_f32_e32 v29, 1.0, v29
	v_add_f32_e32 v28, 1.0, v28
	v_rcp_f32_e32 v32, v29
	v_add_f32_e32 v29, 1.0, v33
	v_rcp_f32_e32 v28, v28
	v_rcp_f32_e32 v29, v29
	v_add_f32_e32 v33, 1.0, v34
	v_rcp_f32_e32 v33, v33
	v_pk_mul_f32 v[20:21], v[16:17], v[20:21]
	v_pk_mul_f32 v[16:17], v[30:31], v[28:29]
	s_nop 0
	v_pk_mul_f32 v[26:27], v[26:27], v[16:17]
	v_pk_mul_f32 v[16:17], v[22:23], v[32:33]
	s_nop 0
	v_pk_mul_f32 v[22:23], v[18:19], v[16:17]
	v_cvt_pk_bf16_f32 v18, v20, v21
	v_lshl_add_u64 v[20:21], s[20:21], 0, v[150:151]
	v_cvt_pk_bf16_f32 v16, v24, v25
	v_cvt_pk_bf16_f32 v17, v26, v27
	v_cvt_pk_bf16_f32 v19, v22, v23
	v_lshl_add_u64 v[20:21], v[20:21], 0, v[136:137]
	global_store_dwordx4 v[20:21], v[16:19], off nt
	s_nop 1
	v_mul_f32_e32 v16, 0xbfb8aa3b, v12
	v_mul_f32_e32 v17, 0xbfb8aa3b, v4
	v_mul_f32_e32 v18, 0xbfb8aa3b, v13
	v_exp_f32_e32 v16, v16
	v_exp_f32_e32 v17, v17
	v_exp_f32_e32 v18, v18
	v_add_f32_e32 v16, 1.0, v16
	v_add_f32_e32 v19, 1.0, v17
	v_add_f32_e32 v17, 1.0, v18
	v_rcp_f32_e32 v16, v16
	v_rcp_f32_e32 v17, v17
	v_mul_f32_e32 v18, 0xbfb8aa3b, v5
	v_exp_f32_e32 v20, v18
	v_rcp_f32_e32 v18, v19
	v_pk_mul_f32 v[12:13], v[12:13], v[16:17]
	v_mul_f32_e32 v16, 0xbfb8aa3b, v15
	v_pk_mul_f32 v[8:9], v[8:9], v[12:13]
	v_add_f32_e32 v12, 1.0, v20
	v_rcp_f32_e32 v19, v12
	v_mul_f32_e32 v13, 0xbfb8aa3b, v6
	v_mul_f32_e32 v12, 0xbfb8aa3b, v14
	v_exp_f32_e32 v13, v13
	v_exp_f32_e32 v12, v12
	v_exp_f32_e32 v17, v16
	v_mul_f32_e32 v16, 0xbfb8aa3b, v7
	v_pk_mul_f32 v[4:5], v[4:5], v[18:19]
	v_exp_f32_e32 v18, v16
	v_add_f32_e32 v13, 1.0, v13
	v_add_f32_e32 v12, 1.0, v12
	v_rcp_f32_e32 v16, v13
	v_add_f32_e32 v13, 1.0, v17
	v_rcp_f32_e32 v12, v12
	v_rcp_f32_e32 v13, v13
	v_add_f32_e32 v17, 1.0, v18
	v_rcp_f32_e32 v17, v17
	v_pk_mul_f32 v[4:5], v[0:1], v[4:5]
	v_pk_mul_f32 v[0:1], v[14:15], v[12:13]
	s_nop 0
	v_pk_mul_f32 v[10:11], v[10:11], v[0:1]
	v_pk_mul_f32 v[0:1], v[6:7], v[16:17]
	s_nop 0
	v_pk_mul_f32 v[6:7], v[2:3], v[0:1]
	v_cvt_pk_bf16_f32 v2, v4, v5
	v_lshl_add_u64 v[4:5], s[20:21], 0, v[152:153]
	v_cvt_pk_bf16_f32 v0, v8, v9
	v_cvt_pk_bf16_f32 v1, v10, v11
	v_cvt_pk_bf16_f32 v3, v6, v7
	v_lshl_add_u64 v[4:5], v[4:5], 0, v[136:137]
	global_store_dwordx4 v[4:5], v[0:3], off nt
	s_cbranch_vccnz .LBB0_133
	s_andn2_b64 vcc, exec, s[12:13]
	s_cbranch_vccnz .LBB0_132
	s_barrier
	s_branch .LBB0_132

.LBB0_973:
	v_lshl_add_u32 v170, s65, 8, v138
	v_ashrrev_i32_e32 v171, 31, v170
	v_lshl_add_u64 v[170:171], v[170:171], 2, s[22:23]
	global_load_dword v169, v[170:171], off
	global_load_dword v172, v[170:171], off offset:64
	global_load_dword v173, v[170:171], off offset:128
	global_load_dword v174, v[170:171], off offset:192
	global_load_dword v175, v[170:171], off offset:512
	global_load_dword v176, v[170:171], off offset:576
	global_load_dword v177, v[170:171], off offset:640
	s_nop 0
	global_load_dword v170, v[170:171], off offset:704
	s_waitcnt vmcnt(0)
	v_fmamk_f32 v169, v169, 0x3a000000, v167
	v_fmamk_f32 v171, v172, 0x3a000000, v167
	v_fmamk_f32 v172, v173, 0x3a000000, v167
	v_fmamk_f32 v173, v174, 0x3a000000, v167
	v_fmamk_f32 v174, v175, 0x3a000000, v167
	v_fmamk_f32 v175, v176, 0x3a000000, v167
	v_mul_f32_e32 v176, 0x4f800000, v169
	v_cmp_gt_f32_e32 vcc, s62, v169
	v_mul_f32_e32 v178, 0x4f800000, v171
	v_cmp_gt_f32_e64 s[2:3], s62, v171
	v_cndmask_b32_e32 v169, v169, v176, vcc
	v_mul_f32_e32 v179, 0x4f800000, v172
	v_cndmask_b32_e64 v171, v171, v178, s[2:3]
	v_cmp_gt_f32_e64 s[4:5], s62, v172
	v_sqrt_f32_e32 v176, v169
	v_mul_f32_e32 v180, 0x4f800000, v173
	v_cndmask_b32_e64 v172, v172, v179, s[4:5]
	v_cmp_gt_f32_e64 s[6:7], s62, v173
	v_sqrt_f32_e32 v178, v171
	v_mul_f32_e32 v181, 0x4f800000, v174
	v_cndmask_b32_e64 v173, v173, v180, s[6:7]
	v_cmp_gt_f32_e64 s[8:9], s62, v174
	v_sqrt_f32_e32 v179, v172
	v_mul_f32_e32 v182, 0x4f800000, v175
	v_cndmask_b32_e64 v174, v174, v181, s[8:9]
	v_cmp_gt_f32_e64 s[10:11], s62, v175
	v_sqrt_f32_e32 v180, v173
	v_sqrt_f32_e32 v181, v174
	v_cndmask_b32_e64 v175, v175, v182, s[10:11]
	v_add_u32_e32 v182, -1, v176
	v_add_u32_e32 v184, -1, v178
	v_fma_f32 v192, -v182, v176, v169
	v_add_u32_e32 v183, 1, v176
	v_add_u32_e32 v186, -1, v179
	v_fma_f32 v194, -v184, v178, v171
	v_cmp_ge_f32_e64 s[12:13], 0, v192
	v_add_u32_e32 v185, 1, v178
	v_add_u32_e32 v188, -1, v180
	v_fma_f32 v193, -v183, v176, v169
	v_fma_f32 v196, -v186, v179, v172
	v_cndmask_b32_e64 v176, v176, v182, s[12:13]
	v_cmp_ge_f32_e64 s[12:13], 0, v194
	v_add_u32_e32 v187, 1, v179
	v_add_u32_e32 v190, -1, v181
	v_fma_f32 v195, -v185, v178, v171
	v_fma_f32 v198, -v188, v180, v173
	v_cndmask_b32_e64 v178, v178, v184, s[12:13]
	v_cmp_ge_f32_e64 s[12:13], 0, v196
	v_add_u32_e32 v189, 1, v180
	v_fma_f32 v197, -v187, v179, v172
	v_fma_f32 v200, -v190, v181, v174
	v_cndmask_b32_e64 v179, v179, v186, s[12:13]
	v_cmp_ge_f32_e64 s[12:13], 0, v198
	v_add_u32_e32 v191, 1, v181
	v_fma_f32 v199, -v189, v180, v173
	v_cndmask_b32_e64 v180, v180, v188, s[12:13]
	v_cmp_ge_f32_e64 s[12:13], 0, v200
	v_fma_f32 v201, -v191, v181, v174
	v_fmamk_f32 v170, v170, 0x3a000000, v167
	v_cndmask_b32_e64 v181, v181, v190, s[12:13]
	v_cmp_lt_f32_e64 s[12:13], 0, v193
	s_nop 1
	v_cndmask_b32_e64 v176, v176, v183, s[12:13]
	v_cmp_lt_f32_e64 s[12:13], 0, v195
	v_mul_f32_e32 v182, 0x37800000, v176
	v_cndmask_b32_e32 v176, v176, v182, vcc
	v_cndmask_b32_e64 v178, v178, v185, s[12:13]
	v_cmp_lt_f32_e64 s[12:13], 0, v197
	v_mul_f32_e32 v183, 0x37800000, v178
	v_cmp_class_f32_e32 vcc, v169, v168
	v_cndmask_b32_e64 v179, v179, v187, s[12:13]
	v_cmp_lt_f32_e64 s[12:13], 0, v199
	v_mul_f32_e32 v184, 0x37800000, v179
	v_cndmask_b32_e64 v178, v178, v183, s[2:3]
	v_cndmask_b32_e64 v180, v180, v189, s[12:13]
	v_cmp_lt_f32_e64 s[12:13], 0, v201
	v_cndmask_b32_e32 v176, v176, v169, vcc
	v_cmp_class_f32_e32 vcc, v171, v168
	v_sqrt_f32_e32 v169, v175
	v_cndmask_b32_e64 v181, v181, v191, s[12:13]
	v_mul_f32_e32 v185, 0x37800000, v180
	v_cndmask_b32_e64 v179, v179, v184, s[4:5]
	v_cndmask_b32_e32 v182, v178, v171, vcc
	v_cmp_class_f32_e32 vcc, v172, v168
	v_mul_f32_e32 v186, 0x37800000, v181
	v_cndmask_b32_e64 v180, v180, v185, s[6:7]
	v_cndmask_b32_e32 v183, v179, v172, vcc
	v_cmp_class_f32_e32 vcc, v173, v168
	v_cndmask_b32_e64 v171, v181, v186, s[8:9]
	v_cmp_class_f32_e64 s[2:3], v175, v168
	v_cndmask_b32_e32 v173, v180, v173, vcc
	v_cmp_class_f32_e32 vcc, v174, v168
	s_mul_i32 s6, s65, 0x58
	s_mul_hi_i32 s5, s65, 0x58
	v_cndmask_b32_e32 v172, v171, v174, vcc
	v_add_u32_e32 v171, -1, v169
	v_fma_f32 v174, -v171, v169, v175
	v_cmp_ge_f32_e32 vcc, 0, v174
	v_add_u32_e32 v174, 1, v169
	s_nop 0
	v_cndmask_b32_e32 v171, v169, v171, vcc
	v_fma_f32 v169, -v174, v169, v175
	v_cmp_lt_f32_e32 vcc, 0, v169
	s_nop 1
	v_cndmask_b32_e32 v169, v171, v174, vcc
	v_fmamk_f32 v174, v177, 0x3a000000, v167
	v_mul_f32_e32 v177, 0x4f800000, v174
	v_cmp_gt_f32_e32 vcc, s62, v174
	v_mul_f32_e32 v171, 0x37800000, v169
	v_cndmask_b32_e64 v169, v169, v171, s[10:11]
	v_cndmask_b32_e32 v174, v174, v177, vcc
	v_sqrt_f32_e32 v177, v174
	v_cndmask_b32_e64 v171, v169, v175, s[2:3]
	v_add_u32_e32 v169, -1, v177
	v_fma_f32 v175, -v169, v177, v174
	v_cmp_ge_f32_e64 s[2:3], 0, v175
	v_add_u32_e32 v175, 1, v177
	s_nop 0
	v_cndmask_b32_e64 v169, v177, v169, s[2:3]
	v_fma_f32 v177, -v175, v177, v174
	v_cmp_lt_f32_e64 s[2:3], 0, v177
	v_mul_f32_e32 v177, 0x4f800000, v170
	s_nop 0
	v_cndmask_b32_e64 v169, v169, v175, s[2:3]
	v_cmp_gt_f32_e64 s[2:3], s62, v170
	v_mul_f32_e32 v175, 0x37800000, v169
	v_cndmask_b32_e32 v169, v169, v175, vcc
	v_cndmask_b32_e64 v177, v170, v177, s[2:3]
	v_sqrt_f32_e32 v178, v177
	v_cmp_class_f32_e32 vcc, v174, v168
	s_nop 1
	v_cndmask_b32_e32 v170, v169, v174, vcc
	v_add_u32_e32 v169, -1, v178
	v_fma_f32 v174, -v169, v178, v177
	v_cmp_ge_f32_e32 vcc, 0, v174
	v_add_u32_e32 v174, 1, v178
	v_fma_f32 v175, -v174, v178, v177
	v_cndmask_b32_e32 v169, v178, v169, vcc
	v_cmp_lt_f32_e32 vcc, 0, v175
	s_nop 1
	v_cndmask_b32_e32 v169, v169, v174, vcc
	v_mul_f32_e32 v174, 0x37800000, v169
	v_cndmask_b32_e64 v169, v169, v174, s[2:3]
	s_lshl_b32 s2, s66, 1
	s_or_b32 s4, s2, s53
	v_div_scale_f32 v174, s[2:3], v176, v176, 1.0
	v_rcp_f32_e32 v175, v174
	v_cmp_class_f32_e32 vcc, v177, v168
	s_ashr_i32 s3, s4, 31
	s_add_u32 s2, s6, s4
	v_cndmask_b32_e32 v169, v169, v177, vcc
	v_fma_f32 v177, -v174, v175, 1.0
	v_fmac_f32_e32 v175, v177, v175
	v_div_scale_f32 v177, vcc, 1.0, v176, 1.0
	v_mul_f32_e32 v178, v177, v175
	v_fma_f32 v179, -v174, v178, v177
	v_fmac_f32_e32 v178, v179, v175
	v_fma_f32 v174, -v174, v178, v177
	v_div_fmas_f32 v174, v174, v175, v178
	v_div_fixup_f32 v174, v174, v176, 1.0
	v_pk_mul_f32 v[124:125], v[124:125], v[174:175] op_sel_hi:[1,0]
	s_addc_u32 s3, s5, s3
	v_mul_f32_e32 v175, 0xbfb8aa3b, v124
	v_exp_f32_e32 v175, v175
	v_mul_f32_e32 v176, 0xbfb8aa3b, v125
	v_exp_f32_e32 v177, v176
	s_lshl_b64 s[2:3], s[2:3], 15
	v_add_f32_e32 v175, 1.0, v175
	v_rcp_f32_e32 v176, v175
	v_add_f32_e32 v175, 1.0, v177
	v_pk_mul_f32 v[120:121], v[120:121], v[174:175] op_sel_hi:[1,0]
	s_add_u32 s2, s47, s2
	v_mul_f32_e32 v177, 0xbfb8aa3b, v120
	v_exp_f32_e32 v178, v177
	v_mul_f32_e32 v177, 0xbfb8aa3b, v121
	v_exp_f32_e32 v179, v177
	v_rcp_f32_e32 v177, v175
	v_add_f32_e32 v175, 1.0, v178
	v_rcp_f32_e32 v178, v175
	v_add_f32_e32 v175, 1.0, v179
	v_pk_mul_f32 v[124:125], v[124:125], v[176:177]
	v_pk_mul_f32 v[116:117], v[116:117], v[174:175] op_sel_hi:[1,0]
	v_rcp_f32_e32 v179, v175
	v_pk_mul_f32 v[116:117], v[116:117], v[124:125]
	v_pk_mul_f32 v[124:125], v[126:127], v[174:175] op_sel_hi:[1,0]
	v_pk_mul_f32 v[112:113], v[112:113], v[174:175] op_sel_hi:[1,0]
	v_mul_f32_e32 v126, 0xbfb8aa3b, v124
	v_mul_f32_e32 v127, 0xbfb8aa3b, v125
	v_exp_f32_e32 v126, v126
	v_exp_f32_e32 v127, v127
	v_pk_mul_f32 v[120:121], v[120:121], v[178:179]
	v_pk_mul_f32 v[122:123], v[122:123], v[174:175] op_sel_hi:[1,0]
	v_pk_mul_f32 v[120:121], v[112:113], v[120:121]
	v_add_f32_e32 v112, 1.0, v126
	v_add_f32_e32 v113, 1.0, v127
	v_mul_f32_e32 v126, 0xbfb8aa3b, v122
	v_mul_f32_e32 v127, 0xbfb8aa3b, v123
	v_exp_f32_e32 v126, v126
	v_exp_f32_e32 v127, v127
	v_rcp_f32_e32 v112, v112
	v_rcp_f32_e32 v113, v113
	v_add_f32_e32 v126, 1.0, v126
	v_add_f32_e32 v127, 1.0, v127
	v_rcp_f32_e32 v126, v126
	v_rcp_f32_e32 v127, v127
	v_pk_mul_f32 v[112:113], v[124:125], v[112:113]
	v_pk_mul_f32 v[118:119], v[118:119], v[174:175] op_sel_hi:[1,0]
	v_pk_mul_f32 v[114:115], v[114:115], v[174:175] op_sel_hi:[1,0]
	v_pk_mul_f32 v[118:119], v[118:119], v[112:113]
	v_pk_mul_f32 v[112:113], v[122:123], v[126:127]
	s_addc_u32 s3, s48, s3
	v_pk_mul_f32 v[122:123], v[114:115], v[112:113]
	v_cvt_pk_bf16_f32 v113, v118, v119
	v_div_scale_f32 v118, s[4:5], v182, v182, 1.0
	v_rcp_f32_e32 v119, v118
	v_cvt_pk_bf16_f32 v114, v120, v121
	v_cvt_pk_bf16_f32 v115, v122, v123
	v_cvt_pk_bf16_f32 v112, v116, v117
	v_fma_f32 v120, -v118, v119, 1.0
	v_fmac_f32_e32 v119, v120, v119
	v_div_scale_f32 v120, vcc, 1.0, v182, 1.0
	v_mul_f32_e32 v121, v120, v119
	v_fma_f32 v122, -v118, v121, v120
	v_fmac_f32_e32 v121, v122, v119
	v_fma_f32 v118, -v118, v121, v120
	v_div_fmas_f32 v118, v118, v119, v121
	v_div_fixup_f32 v118, v118, v182, 1.0
	v_pk_mul_f32 v[108:109], v[108:109], v[118:119] op_sel_hi:[1,0]
	v_lshl_add_u64 v[116:117], s[2:3], 0, v[140:141]
	v_mul_f32_e32 v119, 0xbfb8aa3b, v108
	v_mul_f32_e32 v120, 0xbfb8aa3b, v109
	v_exp_f32_e32 v119, v119
	v_exp_f32_e32 v120, v120
	v_lshl_add_u64 v[116:117], v[116:117], 0, v[136:137]
	global_store_dwordx4 v[116:117], v[112:115], off nt
	v_pk_mul_f32 v[104:105], v[104:105], v[118:119] op_sel_hi:[1,0]
	v_pk_mul_f32 v[100:101], v[100:101], v[118:119] op_sel_hi:[1,0]
	v_add_f32_e32 v112, 1.0, v119
	v_add_f32_e32 v113, 1.0, v120
	v_rcp_f32_e32 v112, v112
	v_mul_f32_e32 v114, 0xbfb8aa3b, v104
	v_mul_f32_e32 v115, 0xbfb8aa3b, v105
	v_rcp_f32_e32 v113, v113
	v_exp_f32_e32 v114, v114
	v_exp_f32_e32 v115, v115
	v_pk_mul_f32 v[96:97], v[96:97], v[118:119] op_sel_hi:[1,0]
	v_pk_mul_f32 v[108:109], v[108:109], v[112:113]
	v_add_f32_e32 v114, 1.0, v114
	v_add_f32_e32 v115, 1.0, v115
	v_pk_mul_f32 v[100:101], v[100:101], v[108:109]
	v_pk_mul_f32 v[108:109], v[110:111], v[118:119] op_sel_hi:[1,0]
	v_rcp_f32_e32 v114, v114
	v_rcp_f32_e32 v115, v115
	v_mul_f32_e32 v110, 0xbfb8aa3b, v108
	v_mul_f32_e32 v111, 0xbfb8aa3b, v109
	v_exp_f32_e32 v110, v110
	v_exp_f32_e32 v111, v111
	v_pk_mul_f32 v[104:105], v[104:105], v[114:115]
	v_pk_mul_f32 v[106:107], v[106:107], v[118:119] op_sel_hi:[1,0]
	v_pk_mul_f32 v[104:105], v[96:97], v[104:105]
	v_add_f32_e32 v96, 1.0, v110
	v_add_f32_e32 v97, 1.0, v111
	v_mul_f32_e32 v110, 0xbfb8aa3b, v106
	v_mul_f32_e32 v111, 0xbfb8aa3b, v107
	v_exp_f32_e32 v110, v110
	v_exp_f32_e32 v111, v111
	v_rcp_f32_e32 v96, v96
	v_rcp_f32_e32 v97, v97
	v_add_f32_e32 v110, 1.0, v110
	v_add_f32_e32 v111, 1.0, v111
	v_rcp_f32_e32 v110, v110
	v_rcp_f32_e32 v111, v111
	v_pk_mul_f32 v[96:97], v[108:109], v[96:97]
	v_pk_mul_f32 v[102:103], v[102:103], v[118:119] op_sel_hi:[1,0]
	v_pk_mul_f32 v[98:99], v[98:99], v[118:119] op_sel_hi:[1,0]
	v_pk_mul_f32 v[102:103], v[102:103], v[96:97]
	v_pk_mul_f32 v[96:97], v[106:107], v[110:111]
	s_nop 0
	v_pk_mul_f32 v[106:107], v[98:99], v[96:97]
	v_cvt_pk_bf16_f32 v97, v102, v103
	v_div_scale_f32 v102, s[4:5], v183, v183, 1.0
	v_rcp_f32_e32 v103, v102
	v_cvt_pk_bf16_f32 v98, v104, v105
	v_cvt_pk_bf16_f32 v99, v106, v107
	v_cvt_pk_bf16_f32 v96, v100, v101
	v_fma_f32 v104, -v102, v103, 1.0
	v_fmac_f32_e32 v103, v104, v103
	v_div_scale_f32 v104, vcc, 1.0, v183, 1.0
	v_mul_f32_e32 v105, v104, v103
	v_fma_f32 v106, -v102, v105, v104
	v_fmac_f32_e32 v105, v106, v103
	v_fma_f32 v102, -v102, v105, v104
	v_div_fmas_f32 v102, v102, v103, v105
	v_div_fixup_f32 v102, v102, v183, 1.0
	v_pk_mul_f32 v[92:93], v[92:93], v[102:103] op_sel_hi:[1,0]
	v_lshl_add_u64 v[100:101], s[2:3], 0, v[142:143]
	v_mul_f32_e32 v103, 0xbfb8aa3b, v92
	v_mul_f32_e32 v104, 0xbfb8aa3b, v93
	v_exp_f32_e32 v103, v103
	v_exp_f32_e32 v104, v104
	v_lshl_add_u64 v[100:101], v[100:101], 0, v[136:137]
	global_store_dwordx4 v[100:101], v[96:99], off nt
	v_pk_mul_f32 v[88:89], v[88:89], v[102:103] op_sel_hi:[1,0]
	v_pk_mul_f32 v[84:85], v[84:85], v[102:103] op_sel_hi:[1,0]
	v_add_f32_e32 v96, 1.0, v103
	v_add_f32_e32 v97, 1.0, v104
	v_rcp_f32_e32 v96, v96
	v_mul_f32_e32 v98, 0xbfb8aa3b, v88
	v_mul_f32_e32 v99, 0xbfb8aa3b, v89
	v_rcp_f32_e32 v97, v97
	v_exp_f32_e32 v98, v98
	v_exp_f32_e32 v99, v99
	v_pk_mul_f32 v[80:81], v[80:81], v[102:103] op_sel_hi:[1,0]
	v_pk_mul_f32 v[92:93], v[92:93], v[96:97]
	v_add_f32_e32 v98, 1.0, v98
	v_add_f32_e32 v99, 1.0, v99
	v_pk_mul_f32 v[84:85], v[84:85], v[92:93]
	v_pk_mul_f32 v[92:93], v[94:95], v[102:103] op_sel_hi:[1,0]
	v_rcp_f32_e32 v98, v98
	v_rcp_f32_e32 v99, v99
	v_mul_f32_e32 v94, 0xbfb8aa3b, v92
	v_mul_f32_e32 v95, 0xbfb8aa3b, v93
	v_exp_f32_e32 v94, v94
	v_exp_f32_e32 v95, v95
	v_pk_mul_f32 v[88:89], v[88:89], v[98:99]
	v_pk_mul_f32 v[90:91], v[90:91], v[102:103] op_sel_hi:[1,0]
	v_pk_mul_f32 v[88:89], v[80:81], v[88:89]
	v_add_f32_e32 v80, 1.0, v94
	v_add_f32_e32 v81, 1.0, v95
	v_mul_f32_e32 v94, 0xbfb8aa3b, v90
	v_mul_f32_e32 v95, 0xbfb8aa3b, v91
	v_exp_f32_e32 v94, v94
	v_exp_f32_e32 v95, v95
	v_rcp_f32_e32 v80, v80
	v_rcp_f32_e32 v81, v81
	v_add_f32_e32 v94, 1.0, v94
	v_add_f32_e32 v95, 1.0, v95
	v_rcp_f32_e32 v94, v94
	v_rcp_f32_e32 v95, v95
	v_pk_mul_f32 v[80:81], v[92:93], v[80:81]
	v_pk_mul_f32 v[86:87], v[86:87], v[102:103] op_sel_hi:[1,0]
	v_pk_mul_f32 v[82:83], v[82:83], v[102:103] op_sel_hi:[1,0]
	v_pk_mul_f32 v[86:87], v[86:87], v[80:81]
	v_pk_mul_f32 v[80:81], v[90:91], v[94:95]
	s_nop 0
	v_pk_mul_f32 v[90:91], v[82:83], v[80:81]
	v_cvt_pk_bf16_f32 v81, v86, v87
	v_div_scale_f32 v86, s[4:5], v173, v173, 1.0
	v_rcp_f32_e32 v87, v86
	v_cvt_pk_bf16_f32 v82, v88, v89
	v_cvt_pk_bf16_f32 v83, v90, v91
	v_cvt_pk_bf16_f32 v80, v84, v85
	v_fma_f32 v88, -v86, v87, 1.0
	v_fmac_f32_e32 v87, v88, v87
	v_div_scale_f32 v88, vcc, 1.0, v173, 1.0
	v_mul_f32_e32 v89, v88, v87
	v_fma_f32 v90, -v86, v89, v88
	v_fmac_f32_e32 v89, v90, v87
	v_fma_f32 v86, -v86, v89, v88
	v_div_fmas_f32 v86, v86, v87, v89
	v_div_fixup_f32 v86, v86, v173, 1.0
	v_pk_mul_f32 v[76:77], v[76:77], v[86:87] op_sel_hi:[1,0]
	v_lshl_add_u64 v[84:85], s[2:3], 0, v[144:145]
	v_mul_f32_e32 v87, 0xbfb8aa3b, v76
	v_mul_f32_e32 v88, 0xbfb8aa3b, v77
	v_exp_f32_e32 v87, v87
	v_exp_f32_e32 v88, v88
	v_lshl_add_u64 v[84:85], v[84:85], 0, v[136:137]
	global_store_dwordx4 v[84:85], v[80:83], off nt
	v_pk_mul_f32 v[72:73], v[72:73], v[86:87] op_sel_hi:[1,0]
	v_pk_mul_f32 v[68:69], v[68:69], v[86:87] op_sel_hi:[1,0]
	v_add_f32_e32 v80, 1.0, v87
	v_add_f32_e32 v81, 1.0, v88
	v_rcp_f32_e32 v80, v80
	v_mul_f32_e32 v82, 0xbfb8aa3b, v72
	v_mul_f32_e32 v83, 0xbfb8aa3b, v73
	v_rcp_f32_e32 v81, v81
	v_exp_f32_e32 v82, v82
	v_exp_f32_e32 v83, v83
	v_pk_mul_f32 v[64:65], v[64:65], v[86:87] op_sel_hi:[1,0]
	v_pk_mul_f32 v[76:77], v[76:77], v[80:81]
	v_add_f32_e32 v82, 1.0, v82
	v_add_f32_e32 v83, 1.0, v83
	v_pk_mul_f32 v[68:69], v[68:69], v[76:77]
	v_pk_mul_f32 v[76:77], v[78:79], v[86:87] op_sel_hi:[1,0]
	v_rcp_f32_e32 v82, v82
	v_rcp_f32_e32 v83, v83
	v_mul_f32_e32 v78, 0xbfb8aa3b, v76
	v_mul_f32_e32 v79, 0xbfb8aa3b, v77
	v_exp_f32_e32 v78, v78
	v_exp_f32_e32 v79, v79
	v_pk_mul_f32 v[72:73], v[72:73], v[82:83]
	v_pk_mul_f32 v[74:75], v[74:75], v[86:87] op_sel_hi:[1,0]
	v_pk_mul_f32 v[72:73], v[64:65], v[72:73]
	v_add_f32_e32 v64, 1.0, v78
	v_add_f32_e32 v65, 1.0, v79
	v_mul_f32_e32 v78, 0xbfb8aa3b, v74
	v_mul_f32_e32 v79, 0xbfb8aa3b, v75
	v_exp_f32_e32 v78, v78
	v_exp_f32_e32 v79, v79
	v_rcp_f32_e32 v64, v64
	v_rcp_f32_e32 v65, v65
	v_add_f32_e32 v78, 1.0, v78
	v_add_f32_e32 v79, 1.0, v79
	v_rcp_f32_e32 v78, v78
	v_rcp_f32_e32 v79, v79
	v_pk_mul_f32 v[64:65], v[76:77], v[64:65]
	v_pk_mul_f32 v[70:71], v[70:71], v[86:87] op_sel_hi:[1,0]
	v_pk_mul_f32 v[66:67], v[66:67], v[86:87] op_sel_hi:[1,0]
	v_pk_mul_f32 v[70:71], v[70:71], v[64:65]
	v_pk_mul_f32 v[64:65], v[74:75], v[78:79]
	s_nop 0
	v_pk_mul_f32 v[74:75], v[66:67], v[64:65]
	v_cvt_pk_bf16_f32 v65, v70, v71
	v_div_scale_f32 v70, s[4:5], v172, v172, 1.0
	v_rcp_f32_e32 v71, v70
	v_cvt_pk_bf16_f32 v66, v72, v73
	v_cvt_pk_bf16_f32 v67, v74, v75
	v_cvt_pk_bf16_f32 v64, v68, v69
	v_fma_f32 v72, -v70, v71, 1.0
	v_fmac_f32_e32 v71, v72, v71
	v_div_scale_f32 v72, vcc, 1.0, v172, 1.0
	v_mul_f32_e32 v73, v72, v71
	v_fma_f32 v74, -v70, v73, v72
	v_fmac_f32_e32 v73, v74, v71
	v_fma_f32 v70, -v70, v73, v72
	v_div_fmas_f32 v70, v70, v71, v73
	v_div_fixup_f32 v70, v70, v172, 1.0
	v_pk_mul_f32 v[60:61], v[60:61], v[70:71] op_sel_hi:[1,0]
	v_lshl_add_u64 v[68:69], s[2:3], 0, v[146:147]
	v_mul_f32_e32 v71, 0xbfb8aa3b, v60
	v_mul_f32_e32 v72, 0xbfb8aa3b, v61
	v_exp_f32_e32 v71, v71
	v_exp_f32_e32 v72, v72
	v_lshl_add_u64 v[68:69], v[68:69], 0, v[136:137]
	global_store_dwordx4 v[68:69], v[64:67], off nt
	v_pk_mul_f32 v[56:57], v[56:57], v[70:71] op_sel_hi:[1,0]
	v_pk_mul_f32 v[52:53], v[52:53], v[70:71] op_sel_hi:[1,0]
	v_add_f32_e32 v64, 1.0, v71
	v_add_f32_e32 v65, 1.0, v72
	v_rcp_f32_e32 v64, v64
	v_mul_f32_e32 v66, 0xbfb8aa3b, v56
	v_mul_f32_e32 v67, 0xbfb8aa3b, v57
	v_rcp_f32_e32 v65, v65
	v_exp_f32_e32 v66, v66
	v_exp_f32_e32 v67, v67
	v_pk_mul_f32 v[48:49], v[48:49], v[70:71] op_sel_hi:[1,0]
	v_pk_mul_f32 v[60:61], v[60:61], v[64:65]
	v_add_f32_e32 v66, 1.0, v66
	v_add_f32_e32 v67, 1.0, v67
	v_pk_mul_f32 v[52:53], v[52:53], v[60:61]
	v_pk_mul_f32 v[60:61], v[62:63], v[70:71] op_sel_hi:[1,0]
	v_rcp_f32_e32 v66, v66
	v_rcp_f32_e32 v67, v67
	v_mul_f32_e32 v62, 0xbfb8aa3b, v60
	v_mul_f32_e32 v63, 0xbfb8aa3b, v61
	v_exp_f32_e32 v62, v62
	v_exp_f32_e32 v63, v63
	v_pk_mul_f32 v[56:57], v[56:57], v[66:67]
	v_pk_mul_f32 v[58:59], v[58:59], v[70:71] op_sel_hi:[1,0]
	v_pk_mul_f32 v[56:57], v[48:49], v[56:57]
	v_add_f32_e32 v48, 1.0, v62
	v_add_f32_e32 v49, 1.0, v63
	v_mul_f32_e32 v62, 0xbfb8aa3b, v58
	v_mul_f32_e32 v63, 0xbfb8aa3b, v59
	v_exp_f32_e32 v62, v62
	v_exp_f32_e32 v63, v63
	v_rcp_f32_e32 v48, v48
	v_rcp_f32_e32 v49, v49
	v_add_f32_e32 v62, 1.0, v62
	v_add_f32_e32 v63, 1.0, v63
	v_rcp_f32_e32 v62, v62
	v_rcp_f32_e32 v63, v63
	v_pk_mul_f32 v[48:49], v[60:61], v[48:49]
	v_pk_mul_f32 v[54:55], v[54:55], v[70:71] op_sel_hi:[1,0]
	v_pk_mul_f32 v[50:51], v[50:51], v[70:71] op_sel_hi:[1,0]
	v_pk_mul_f32 v[54:55], v[54:55], v[48:49]
	v_pk_mul_f32 v[48:49], v[58:59], v[62:63]
	s_nop 0
	v_pk_mul_f32 v[58:59], v[50:51], v[48:49]
	v_cvt_pk_bf16_f32 v49, v54, v55
	v_div_scale_f32 v54, s[4:5], v171, v171, 1.0
	v_rcp_f32_e32 v55, v54
	v_cvt_pk_bf16_f32 v50, v56, v57
	v_cvt_pk_bf16_f32 v51, v58, v59
	v_cvt_pk_bf16_f32 v48, v52, v53
	v_fma_f32 v56, -v54, v55, 1.0
	v_fmac_f32_e32 v55, v56, v55
	v_div_scale_f32 v56, vcc, 1.0, v171, 1.0
	v_mul_f32_e32 v57, v56, v55
	v_fma_f32 v58, -v54, v57, v56
	v_fmac_f32_e32 v57, v58, v55
	v_fma_f32 v54, -v54, v57, v56
	v_div_fmas_f32 v54, v54, v55, v57
	v_div_fixup_f32 v54, v54, v171, 1.0
	v_pk_mul_f32 v[44:45], v[44:45], v[54:55] op_sel_hi:[1,0]
	v_lshl_add_u64 v[52:53], s[2:3], 0, v[148:149]
	v_mul_f32_e32 v55, 0xbfb8aa3b, v44
	v_mul_f32_e32 v56, 0xbfb8aa3b, v45
	v_exp_f32_e32 v55, v55
	v_exp_f32_e32 v56, v56
	v_lshl_add_u64 v[52:53], v[52:53], 0, v[136:137]
	global_store_dwordx4 v[52:53], v[48:51], off nt
	v_pk_mul_f32 v[40:41], v[40:41], v[54:55] op_sel_hi:[1,0]
	v_pk_mul_f32 v[36:37], v[36:37], v[54:55] op_sel_hi:[1,0]
	v_add_f32_e32 v48, 1.0, v55
	v_add_f32_e32 v49, 1.0, v56
	v_rcp_f32_e32 v48, v48
	v_mul_f32_e32 v50, 0xbfb8aa3b, v40
	v_mul_f32_e32 v51, 0xbfb8aa3b, v41
	v_rcp_f32_e32 v49, v49
	v_exp_f32_e32 v50, v50
	v_exp_f32_e32 v51, v51
	v_pk_mul_f32 v[32:33], v[32:33], v[54:55] op_sel_hi:[1,0]
	v_pk_mul_f32 v[44:45], v[44:45], v[48:49]
	v_add_f32_e32 v50, 1.0, v50
	v_add_f32_e32 v51, 1.0, v51
	v_pk_mul_f32 v[36:37], v[36:37], v[44:45]
	v_pk_mul_f32 v[44:45], v[46:47], v[54:55] op_sel_hi:[1,0]
	v_rcp_f32_e32 v50, v50
	v_rcp_f32_e32 v51, v51
	v_mul_f32_e32 v46, 0xbfb8aa3b, v44
	v_mul_f32_e32 v47, 0xbfb8aa3b, v45
	v_exp_f32_e32 v46, v46
	v_exp_f32_e32 v47, v47
	v_pk_mul_f32 v[40:41], v[40:41], v[50:51]
	v_pk_mul_f32 v[42:43], v[42:43], v[54:55] op_sel_hi:[1,0]
	v_pk_mul_f32 v[40:41], v[32:33], v[40:41]
	v_add_f32_e32 v32, 1.0, v46
	v_add_f32_e32 v33, 1.0, v47
	v_mul_f32_e32 v46, 0xbfb8aa3b, v42
	v_mul_f32_e32 v47, 0xbfb8aa3b, v43
	v_exp_f32_e32 v46, v46
	v_exp_f32_e32 v47, v47
	v_rcp_f32_e32 v32, v32
	v_rcp_f32_e32 v33, v33
	v_add_f32_e32 v46, 1.0, v46
	v_add_f32_e32 v47, 1.0, v47
	v_rcp_f32_e32 v46, v46
	v_rcp_f32_e32 v47, v47
	v_pk_mul_f32 v[32:33], v[44:45], v[32:33]
	v_pk_mul_f32 v[38:39], v[38:39], v[54:55] op_sel_hi:[1,0]
	v_pk_mul_f32 v[34:35], v[34:35], v[54:55] op_sel_hi:[1,0]
	v_pk_mul_f32 v[38:39], v[38:39], v[32:33]
	v_pk_mul_f32 v[32:33], v[42:43], v[46:47]
	s_nop 0
	v_pk_mul_f32 v[42:43], v[34:35], v[32:33]
	v_cvt_pk_bf16_f32 v33, v38, v39
	v_div_scale_f32 v38, s[4:5], v170, v170, 1.0
	v_rcp_f32_e32 v39, v38
	v_cvt_pk_bf16_f32 v34, v40, v41
	v_cvt_pk_bf16_f32 v35, v42, v43
	v_cvt_pk_bf16_f32 v32, v36, v37
	v_fma_f32 v40, -v38, v39, 1.0
	v_fmac_f32_e32 v39, v40, v39
	v_div_scale_f32 v40, vcc, 1.0, v170, 1.0
	v_mul_f32_e32 v41, v40, v39
	v_fma_f32 v42, -v38, v41, v40
	v_fmac_f32_e32 v41, v42, v39
	v_fma_f32 v38, -v38, v41, v40
	v_div_fmas_f32 v38, v38, v39, v41
	v_div_fixup_f32 v38, v38, v170, 1.0
	v_pk_mul_f32 v[28:29], v[28:29], v[38:39] op_sel_hi:[1,0]
	v_lshl_add_u64 v[36:37], s[2:3], 0, v[150:151]
	v_mul_f32_e32 v39, 0xbfb8aa3b, v28
	v_mul_f32_e32 v40, 0xbfb8aa3b, v29
	v_exp_f32_e32 v39, v39
	v_exp_f32_e32 v40, v40
	v_lshl_add_u64 v[36:37], v[36:37], 0, v[136:137]
	global_store_dwordx4 v[36:37], v[32:35], off nt
	v_pk_mul_f32 v[24:25], v[24:25], v[38:39] op_sel_hi:[1,0]
	v_pk_mul_f32 v[20:21], v[20:21], v[38:39] op_sel_hi:[1,0]
	v_add_f32_e32 v32, 1.0, v39
	v_add_f32_e32 v33, 1.0, v40
	v_rcp_f32_e32 v32, v32
	v_mul_f32_e32 v34, 0xbfb8aa3b, v24
	v_mul_f32_e32 v35, 0xbfb8aa3b, v25
	v_rcp_f32_e32 v33, v33
	v_exp_f32_e32 v34, v34
	v_exp_f32_e32 v35, v35
	v_pk_mul_f32 v[16:17], v[16:17], v[38:39] op_sel_hi:[1,0]
	v_pk_mul_f32 v[28:29], v[28:29], v[32:33]
	v_add_f32_e32 v34, 1.0, v34
	v_add_f32_e32 v35, 1.0, v35
	v_pk_mul_f32 v[20:21], v[20:21], v[28:29]
	v_pk_mul_f32 v[28:29], v[30:31], v[38:39] op_sel_hi:[1,0]
	v_rcp_f32_e32 v34, v34
	v_rcp_f32_e32 v35, v35
	v_mul_f32_e32 v30, 0xbfb8aa3b, v28
	v_mul_f32_e32 v31, 0xbfb8aa3b, v29
	v_exp_f32_e32 v30, v30
	v_exp_f32_e32 v31, v31
	v_pk_mul_f32 v[24:25], v[24:25], v[34:35]
	v_pk_mul_f32 v[26:27], v[26:27], v[38:39] op_sel_hi:[1,0]
	v_pk_mul_f32 v[24:25], v[16:17], v[24:25]
	v_add_f32_e32 v16, 1.0, v30
	v_add_f32_e32 v17, 1.0, v31
	v_mul_f32_e32 v30, 0xbfb8aa3b, v26
	v_mul_f32_e32 v31, 0xbfb8aa3b, v27
	v_exp_f32_e32 v30, v30
	v_exp_f32_e32 v31, v31
	v_rcp_f32_e32 v16, v16
	v_rcp_f32_e32 v17, v17
	v_add_f32_e32 v30, 1.0, v30
	v_add_f32_e32 v31, 1.0, v31
	v_rcp_f32_e32 v30, v30
	v_rcp_f32_e32 v31, v31
	v_pk_mul_f32 v[16:17], v[28:29], v[16:17]
	v_pk_mul_f32 v[22:23], v[22:23], v[38:39] op_sel_hi:[1,0]
	v_pk_mul_f32 v[18:19], v[18:19], v[38:39] op_sel_hi:[1,0]
	v_pk_mul_f32 v[22:23], v[22:23], v[16:17]
	v_pk_mul_f32 v[16:17], v[26:27], v[30:31]
	s_nop 0
	v_pk_mul_f32 v[26:27], v[18:19], v[16:17]
	v_cvt_pk_bf16_f32 v17, v22, v23
	v_div_scale_f32 v22, s[4:5], v169, v169, 1.0
	v_rcp_f32_e32 v23, v22
	v_cvt_pk_bf16_f32 v18, v24, v25
	v_cvt_pk_bf16_f32 v19, v26, v27
	v_cvt_pk_bf16_f32 v16, v20, v21
	v_fma_f32 v24, -v22, v23, 1.0
	v_fmac_f32_e32 v23, v24, v23
	v_div_scale_f32 v24, vcc, 1.0, v169, 1.0
	v_mul_f32_e32 v25, v24, v23
	v_fma_f32 v26, -v22, v25, v24
	v_fmac_f32_e32 v25, v26, v23
	v_fma_f32 v22, -v22, v25, v24
	v_div_fmas_f32 v22, v22, v23, v25
	v_div_fixup_f32 v22, v22, v169, 1.0
	v_pk_mul_f32 v[12:13], v[12:13], v[22:23] op_sel_hi:[1,0]
	v_lshl_add_u64 v[20:21], s[2:3], 0, v[152:153]
	v_mul_f32_e32 v23, 0xbfb8aa3b, v12
	v_mul_f32_e32 v24, 0xbfb8aa3b, v13
	v_exp_f32_e32 v23, v23
	v_exp_f32_e32 v24, v24
	v_lshl_add_u64 v[20:21], v[20:21], 0, v[136:137]
	global_store_dwordx4 v[20:21], v[16:19], off nt
	v_pk_mul_f32 v[8:9], v[8:9], v[22:23] op_sel_hi:[1,0]
	v_pk_mul_f32 v[4:5], v[4:5], v[22:23] op_sel_hi:[1,0]
	v_add_f32_e32 v16, 1.0, v23
	v_add_f32_e32 v17, 1.0, v24
	v_rcp_f32_e32 v16, v16
	v_mul_f32_e32 v18, 0xbfb8aa3b, v8
	v_mul_f32_e32 v19, 0xbfb8aa3b, v9
	v_rcp_f32_e32 v17, v17
	v_exp_f32_e32 v18, v18
	v_exp_f32_e32 v19, v19
	v_pk_mul_f32 v[0:1], v[0:1], v[22:23] op_sel_hi:[1,0]
	v_pk_mul_f32 v[12:13], v[12:13], v[16:17]
	v_add_f32_e32 v18, 1.0, v18
	v_add_f32_e32 v19, 1.0, v19
	v_pk_mul_f32 v[4:5], v[4:5], v[12:13]
	v_pk_mul_f32 v[12:13], v[14:15], v[22:23] op_sel_hi:[1,0]
	v_rcp_f32_e32 v18, v18
	v_rcp_f32_e32 v19, v19
	v_mul_f32_e32 v14, 0xbfb8aa3b, v12
	v_mul_f32_e32 v15, 0xbfb8aa3b, v13
	v_exp_f32_e32 v14, v14
	v_exp_f32_e32 v15, v15
	v_pk_mul_f32 v[8:9], v[8:9], v[18:19]
	v_pk_mul_f32 v[10:11], v[10:11], v[22:23] op_sel_hi:[1,0]
	v_pk_mul_f32 v[8:9], v[0:1], v[8:9]
	v_add_f32_e32 v0, 1.0, v14
	v_add_f32_e32 v1, 1.0, v15
	v_mul_f32_e32 v14, 0xbfb8aa3b, v10
	v_mul_f32_e32 v15, 0xbfb8aa3b, v11
	v_exp_f32_e32 v14, v14
	v_exp_f32_e32 v15, v15
	v_rcp_f32_e32 v0, v0
	v_rcp_f32_e32 v1, v1
	v_add_f32_e32 v14, 1.0, v14
	v_add_f32_e32 v15, 1.0, v15
	v_rcp_f32_e32 v14, v14
	v_rcp_f32_e32 v15, v15
	v_pk_mul_f32 v[0:1], v[12:13], v[0:1]
	v_pk_mul_f32 v[6:7], v[6:7], v[22:23] op_sel_hi:[1,0]
	v_pk_mul_f32 v[2:3], v[2:3], v[22:23] op_sel_hi:[1,0]
	v_pk_mul_f32 v[6:7], v[6:7], v[0:1]
	v_pk_mul_f32 v[0:1], v[10:11], v[14:15]
	s_and_b64 vcc, exec, s[0:1]
	v_pk_mul_f32 v[10:11], v[2:3], v[0:1]
	v_cvt_pk_bf16_f32 v0, v4, v5
	v_lshl_add_u64 v[4:5], s[2:3], 0, v[154:155]
	v_cvt_pk_bf16_f32 v1, v6, v7
	v_cvt_pk_bf16_f32 v2, v8, v9
	v_cvt_pk_bf16_f32 v3, v10, v11
	v_lshl_add_u64 v[4:5], v[4:5], 0, v[136:137]
	s_mov_b64 s[0:1], -1
	global_store_dwordx4 v[4:5], v[0:3], off nt
	s_cbranch_vccnz .LBB0_961
	s_andn2_b64 vcc, exec, s[20:21]
	s_cbranch_vccnz .LBB0_960
	s_barrier
	s_branch .LBB0_960
